# attention unit order: within each round of 256 units the 32 workgroups of an XCD take 32 consecutive units, so overlapping K/V windows of neighbouring query blocks hit that XCD's L2
# speedup vs baseline: 1.0141x; 1.0141x over previous
.LBB0_363:
	s_or_b64 exec, exec, s[0:1]
	v_mov_b32_e32 v6, v254
	s_waitcnt lgkmcnt(0)
	s_barrier
	v_writelane_b32 v255, s94, 18
	v_and_b32_e32 v0, 7, v6
	v_lshlrev_b32_e32 v0, 2, v0
	global_load_dword v135, v0, s[50:51]
	v_readfirstlane_b32 s35, v6
	s_ashr_i32 s34, s35, 6
	s_and_b32 s100, s2, 7
	s_lshl_b32 s100, s100, 5
	s_bfe_u32 s101, s2, 0x50003
	s_or_b32 s100, s100, s101
	s_andn2_b32 s101, s2, 0xff
	s_or_b32 s100, s100, s101
	s_cmpk_gt_i32 s2, 0x5ff
	v_writelane_b32 v255, s95, 19
	s_cselect_b64 s[0:1], -1, 0
	v_writelane_b32 v255, s0, 20
	s_and_b64 vcc, exec, s[0:1]
	s_nop 0
	v_writelane_b32 v255, s1, 21
	s_cbranch_vccz .LBB0_366
	s_add_i32 s0, s100, 0xfffffa00
	s_lshr_b32 s6, s0, 9
	s_bfe_u32 s0, s100, 0x10008
	s_lshl_b32 s1, s100, 6
	s_and_b32 s97, s1, 0x3fc0
	s_lshl_b32 s1, s0, 6
	s_or_b32 s8, s1, 0x200
	s_or_b32 s10, s1, 0x280
	s_lshl_b32 s0, s0, 2
	s_ashr_i32 s1, s35, 7
	s_add_i32 s89, s1, s0
	s_lshl_b32 s0, s34, 5
	s_and_b32 s0, s0, 32
	s_lshl_b32 s4, s89, 6
	s_or_b32 s13, s0, s97
	s_mov_b32 s1, 1
	s_cbranch_execz .LBB0_367
	s_mov_b32 s0, -1
	s_movk_i32 s68, 0x200
	s_movk_i32 s69, 0x7f
	s_movk_i32 s66, 0xc0
	s_mov_b32 s67, 0
	s_mov_b32 s12, s4
	s_mov_b32 s78, 1
	s_branch .LBB0_368

.LBB0_393:
	s_or_b64 exec, exec, s[8:9]
	s_add_i32 s86, s86, s38
	s_waitcnt lgkmcnt(0)
	s_barrier
	s_cmpk_gt_i32 s86, 0x9ff
	s_cselect_b64 s[74:75], -1, 0
	v_mov_b64_e32 v[118:119], v[50:51]
	v_mov_b64_e32 v[122:123], v[54:55]
	v_mov_b64_e32 v[126:127], v[58:59]
	v_mov_b64_e32 v[130:131], v[62:63]
	s_and_b64 vcc, exec, s[74:75]
	s_mov_b32 s76, s6
	s_mov_b32 s90, s1
	s_mov_b32 s91, s67
	s_mov_b32 s87, s97
	s_mov_b32 s88, s13
	s_mov_b32 s80, s89
	s_mov_b32 s94, s69
	s_mov_b32 s92, s68
	s_mov_b32 s95, s12
	s_mov_b32 s93, s0
	s_mov_b32 s96, s78
	v_mov_b64_e32 v[116:117], v[48:49]
	v_mov_b64_e32 v[120:121], v[52:53]
	v_mov_b64_e32 v[124:125], v[56:57]
	v_mov_b64_e32 v[128:129], v[60:61]
	s_cbranch_vccnz .LBB0_417
	s_and_b32 s100, s86, 7
	s_lshl_b32 s100, s100, 5
	s_bfe_u32 s101, s86, 0x50003
	s_or_b32 s100, s100, s101
	s_andn2_b32 s101, s86, 0xff
	s_or_b32 s100, s100, s101
	s_cmpk_gt_i32 s86, 0x5ff
	s_mov_b64 s[46:47], -1
	s_cbranch_scc0 .LBB0_396
	s_add_i32 s7, s100, 0xfffffa00
	s_lshr_b32 s76, s7, 9
	s_bfe_u32 s7, s100, 0x10008
	s_lshl_b32 s8, s100, 6
	s_and_b32 s87, s8, 0x3fc0
	s_lshl_b32 s8, s7, 6
	s_or_b32 s14, s8, 0x200
	s_or_b32 s10, s8, 0x280
	s_lshl_b32 s7, s7, 2
	v_readlane_b32 s8, v255, 24
	s_add_i32 s80, s7, s8
	s_lshl_b32 s8, s80, 6
	s_or_b32 s88, s87, s82
	s_mov_b64 s[46:47], 0

.LBB0_1223:
	s_or_b64 exec, exec, s[0:1]
	v_mov_b32_e32 v6, v254
	s_waitcnt lgkmcnt(0)
	s_barrier
	v_readlane_b32 s0, v255, 20
	v_and_b32_e32 v0, 7, v6
	v_lshlrev_b32_e32 v0, 2, v0
	global_load_dword v135, v0, s[50:51] offset:32
	v_readfirstlane_b32 s35, v6
	v_readlane_b32 s1, v255, 21
	s_ashr_i32 s34, s35, 6
	s_and_b32 s100, s2, 7
	s_lshl_b32 s100, s100, 5
	s_bfe_u32 s101, s2, 0x50003
	s_or_b32 s100, s100, s101
	s_andn2_b32 s101, s2, 0xff
	s_or_b32 s100, s100, s101
	s_and_b64 vcc, exec, s[0:1]
	s_cbranch_vccz .LBB0_1226
	s_add_i32 s0, s100, 0xfffffa00
	s_lshr_b32 s4, s0, 9
	s_bfe_u32 s0, s100, 0x10008
	s_lshl_b32 s1, s100, 6
	s_and_b32 s79, s1, 0x3fc0
	s_lshl_b32 s1, s0, 6
	s_or_b32 s10, s1, 0x200
	s_or_b32 s12, s1, 0x280
	s_lshl_b32 s0, s0, 2
	s_ashr_i32 s1, s35, 7
	s_add_i32 s81, s1, s0
	s_lshl_b32 s0, s34, 5
	s_and_b32 s0, s0, 32
	s_lshl_b32 s8, s81, 6
	s_or_b32 s7, s0, s79
	s_mov_b32 s1, 1
	s_cbranch_execz .LBB0_1227
	s_mov_b32 s0, -1
	s_movk_i32 s66, 0x200
	s_movk_i32 s67, 0x7f
	s_movk_i32 s64, 0xc0
	s_mov_b32 s65, 0
	s_mov_b32 s6, s8
	s_mov_b32 s74, 1
	s_branch .LBB0_1228

.LBB0_1253:
	s_or_b64 exec, exec, s[10:11]
	s_add_i32 s78, s78, s38
	s_waitcnt lgkmcnt(0)
	s_barrier
	s_cmpk_gt_i32 s78, 0x9ff
	s_cselect_b64 s[96:97], -1, 0
	v_mov_b64_e32 v[118:119], v[50:51]
	v_mov_b64_e32 v[122:123], v[54:55]
	v_mov_b64_e32 v[126:127], v[58:59]
	v_mov_b64_e32 v[130:131], v[62:63]
	s_and_b64 vcc, exec, s[96:97]
	s_mov_b32 s40, s4
	s_mov_b32 s84, s1
	s_mov_b32 s85, s65
	s_mov_b32 s70, s79
	s_mov_b32 s80, s7
	s_mov_b32 s69, s81
	s_mov_b32 s90, s67
	s_mov_b32 s86, s66
	s_mov_b32 s91, s6
	s_mov_b32 s87, s0
	s_mov_b32 s68, s74
	v_mov_b64_e32 v[116:117], v[48:49]
	v_mov_b64_e32 v[120:121], v[52:53]
	v_mov_b64_e32 v[124:125], v[56:57]
	v_mov_b64_e32 v[128:129], v[60:61]
	s_cbranch_vccnz .LBB0_1277
	s_and_b32 s100, s78, 7
	s_lshl_b32 s100, s100, 5
	s_bfe_u32 s101, s78, 0x50003
	s_or_b32 s100, s100, s101
	s_andn2_b32 s101, s78, 0xff
	s_or_b32 s100, s100, s101
	s_cmpk_gt_i32 s78, 0x5ff
	s_mov_b64 s[46:47], -1
	s_cbranch_scc0 .LBB0_1256
	s_add_i32 s5, s100, 0xfffffa00
	s_lshr_b32 s40, s5, 9
	s_bfe_u32 s5, s100, 0x10008
	s_lshl_b32 s10, s100, 6
	s_and_b32 s70, s10, 0x3fc0
	s_lshl_b32 s10, s5, 6
	s_or_b32 s14, s10, 0x200
	s_or_b32 s12, s10, 0x280
	s_lshl_b32 s5, s5, 2
	v_readlane_b32 s10, v255, 50
	s_add_i32 s69, s5, s10
	v_readlane_b32 s5, v255, 53
	s_lshl_b32 s10, s69, 6
	s_or_b32 s80, s70, s5
	s_mov_b64 s[46:47], 0

.LBB0_2083:
	s_or_b64 exec, exec, s[0:1]
	v_mov_b32_e32 v6, v254
	s_waitcnt lgkmcnt(0)
	s_barrier
	v_readlane_b32 s0, v255, 20
	v_and_b32_e32 v0, 7, v6
	v_lshlrev_b32_e32 v0, 2, v0
	global_load_dword v135, v0, s[50:51] offset:64
	v_readfirstlane_b32 s35, v6
	v_readlane_b32 s1, v255, 21
	s_ashr_i32 s34, s35, 6
	s_and_b32 s100, s2, 7
	s_lshl_b32 s100, s100, 5
	s_bfe_u32 s101, s2, 0x50003
	s_or_b32 s100, s100, s101
	s_andn2_b32 s101, s2, 0xff
	s_or_b32 s100, s100, s101
	s_and_b64 vcc, exec, s[0:1]
	s_cbranch_vccz .LBB0_2086
	s_add_i32 s0, s100, 0xfffffa00
	s_lshr_b32 s4, s0, 9
	s_bfe_u32 s0, s100, 0x10008
	s_lshl_b32 s1, s100, 6
	s_and_b32 s93, s1, 0x3fc0
	s_lshl_b32 s1, s0, 6
	s_or_b32 s8, s1, 0x200
	s_or_b32 s12, s1, 0x280
	s_lshl_b32 s0, s0, 2
	s_ashr_i32 s1, s35, 7
	s_add_i32 s81, s1, s0
	s_lshl_b32 s0, s34, 5
	s_and_b32 s0, s0, 32
	s_lshl_b32 s10, s81, 6
	s_or_b32 s7, s0, s93
	s_mov_b32 s1, 1
	s_cbranch_execz .LBB0_2087
	s_mov_b32 s0, -1
	s_movk_i32 s66, 0x200
	s_movk_i32 s67, 0x7f
	s_movk_i32 s64, 0xc0
	s_mov_b32 s65, 0
	s_mov_b32 s6, s10
	s_mov_b32 s92, 1
	s_branch .LBB0_2088

.LBB0_2113:
	s_or_b64 exec, exec, s[12:13]
	s_add_i32 s78, s78, s38
	s_waitcnt lgkmcnt(0)
	s_barrier
	s_cmpk_gt_i32 s78, 0x9ff
	s_cselect_b64 s[40:41], -1, 0
	v_mov_b64_e32 v[118:119], v[50:51]
	v_mov_b64_e32 v[122:123], v[54:55]
	v_mov_b64_e32 v[126:127], v[58:59]
	v_mov_b64_e32 v[130:131], v[62:63]
	s_and_b64 vcc, exec, s[40:41]
	s_mov_b32 s74, s4
	s_mov_b32 s84, s1
	s_mov_b32 s85, s65
	s_mov_b32 s79, s93
	s_mov_b32 s80, s7
	s_mov_b32 s68, s81
	s_mov_b32 s90, s67
	s_mov_b32 s86, s66
	s_mov_b32 s91, s6
	s_mov_b32 s87, s0
	s_mov_b32 s70, s92
	v_mov_b64_e32 v[116:117], v[48:49]
	v_mov_b64_e32 v[120:121], v[52:53]
	v_mov_b64_e32 v[124:125], v[56:57]
	v_mov_b64_e32 v[128:129], v[60:61]
	s_cbranch_vccnz .LBB0_2137
	s_and_b32 s100, s78, 7
	s_lshl_b32 s100, s100, 5
	s_bfe_u32 s101, s78, 0x50003
	s_or_b32 s100, s100, s101
	s_andn2_b32 s101, s78, 0xff
	s_or_b32 s100, s100, s101
	s_cmpk_gt_i32 s78, 0x5ff
	s_mov_b64 s[46:47], -1
	s_cbranch_scc0 .LBB0_2116
	s_add_i32 s5, s100, 0xfffffa00
	s_lshr_b32 s74, s5, 9
	s_bfe_u32 s5, s100, 0x10008
	s_lshl_b32 s8, s100, 6
	s_lshl_b32 s12, s5, 6
	s_and_b32 s79, s8, 0x3fc0
	s_or_b32 s8, s12, 0x200
	s_or_b32 s14, s12, 0x280
	s_lshl_b32 s5, s5, 2
	v_readlane_b32 s12, v255, 52
	s_add_i32 s68, s5, s12
	v_readlane_b32 s5, v255, 53
	s_lshl_b32 s12, s68, 6
	s_or_b32 s80, s79, s5
	s_mov_b64 s[46:47], 0

.LBB0_2947:
	s_or_b64 exec, exec, s[0:1]
	v_mov_b32_e32 v6, v254
	s_waitcnt lgkmcnt(0)
	s_barrier
	v_readlane_b32 s0, v255, 20
	v_and_b32_e32 v0, 7, v6
	v_lshlrev_b32_e32 v0, 2, v0
	global_load_dword v135, v0, s[50:51] offset:96
	v_readfirstlane_b32 s19, v6
	v_readlane_b32 s1, v255, 21
	s_ashr_i32 s18, s19, 6
	s_and_b32 s100, s2, 7
	s_lshl_b32 s100, s100, 5
	s_bfe_u32 s101, s2, 0x50003
	s_or_b32 s100, s100, s101
	s_andn2_b32 s101, s2, 0xff
	s_or_b32 s100, s100, s101
	s_and_b64 vcc, exec, s[0:1]
	s_cbranch_vccz .LBB0_2950
	s_add_i32 s0, s100, 0xfffffa00
	s_lshr_b32 s4, s0, 9
	s_bfe_u32 s0, s100, 0x10008
	s_lshl_b32 s1, s100, 6
	s_and_b32 s81, s1, 0x3fc0
	s_lshl_b32 s1, s0, 6
	s_or_b32 s6, s1, 0x200
	s_or_b32 s12, s1, 0x280
	s_lshl_b32 s0, s0, 2
	s_ashr_i32 s1, s19, 7
	s_add_i32 s82, s1, s0
	s_lshl_b32 s0, s18, 5
	s_and_b32 s0, s0, 32
	s_lshl_b32 s10, s82, 6
	s_or_b32 s9, s0, s81
	s_mov_b32 s1, 1
	s_cbranch_execz .LBB0_2951
	s_mov_b32 s0, -1
	s_movk_i32 s54, 0x200
	s_movk_i32 s55, 0x7f
	s_movk_i32 s52, 0xc0
	s_mov_b32 s53, 0
	s_mov_b32 s8, s10
	s_mov_b32 s83, 1
	s_branch .LBB0_2952

.LBB0_2977:
	s_or_b64 exec, exec, s[10:11]
	s_add_i32 s68, s68, s38
	s_waitcnt lgkmcnt(0)
	s_barrier
	s_cmpk_gt_i32 s68, 0x9ff
	s_cselect_b64 s[40:41], -1, 0
	v_mov_b64_e32 v[118:119], v[50:51]
	v_mov_b64_e32 v[122:123], v[54:55]
	v_mov_b64_e32 v[126:127], v[58:59]
	v_mov_b64_e32 v[130:131], v[62:63]
	s_and_b64 vcc, exec, s[40:41]
	s_mov_b32 s50, s4
	s_mov_b32 s72, s1
	s_mov_b32 s73, s53
	s_mov_b32 s69, s81
	s_mov_b32 s70, s9
	s_mov_b32 s71, s82
	s_mov_b32 s78, s55
	s_mov_b32 s74, s54
	s_mov_b32 s79, s8
	s_mov_b32 s75, s0
	s_mov_b32 s80, s83
	v_mov_b64_e32 v[116:117], v[48:49]
	v_mov_b64_e32 v[120:121], v[52:53]
	v_mov_b64_e32 v[124:125], v[56:57]
	v_mov_b64_e32 v[128:129], v[60:61]
	s_cbranch_vccnz .LBB0_3001
	s_and_b32 s100, s68, 7
	s_lshl_b32 s100, s100, 5
	s_bfe_u32 s101, s68, 0x50003
	s_or_b32 s100, s100, s101
	s_andn2_b32 s101, s68, 0xff
	s_or_b32 s100, s100, s101
	s_cmpk_gt_i32 s68, 0x5ff
	s_mov_b64 s[46:47], -1
	s_cbranch_scc0 .LBB0_2980
	s_add_i32 s5, s100, 0xfffffa00
	s_lshr_b32 s50, s5, 9
	s_bfe_u32 s5, s100, 0x10008
	s_lshl_b32 s10, s100, 6
	s_and_b32 s69, s10, 0x3fc0
	s_lshl_b32 s10, s5, 6
	s_lshl_b32 s5, s5, 2
	s_add_i32 s71, s5, s60
	s_or_b32 s16, s10, 0x200
	s_or_b32 s12, s10, 0x280
	s_lshl_b32 s10, s71, 6
	s_or_b32 s70, s69, s64
	s_mov_b64 s[46:47], 0
